# v18 + compiler vmcnt(0) behind each attention K/V DMA group removed (DMA overlaps the wave's own block compute)
# speedup vs baseline: 1.0017x; 1.0017x over previous
; __device__ __forceinline__ void att_block(const bf16x8 (&kf)[4], const bf16x8 (&qf)[4], const bf16x8 (&va)[4], f32x16& o0, f32x16& o1, float& mrun, float& lrun, bool domask, int lo_, int hi_) {
;     f32x16 st;
; #pragma unroll
;     for (int i = 0; i < 16; ++i) st[i] = 0.f;
; #pragma unroll
;     for (int kk = 0; kk < 4; ++kk) st = __builtin_amdgcn_mfma_f32_32x32x16_bf16(kf[kk], qf[kk], st, 0, 0, 0);
;     if (domask) {
;         asm volatile("" : "+v"(lo_), "+v"(hi_));
; #pragma unroll
;         for (int i = 0; i < 16; ++i) { const int ci = (i & 3) + 8 * (i >> 2); st[i] = ((ci - lo_) | (hi_ - ci)) < 0 ? -INFINITY : st[i]; }
;     }
;     float bmax = -INFINITY;
; #pragma unroll
;     for (int i = 0; i < 16; ++i) bmax = fmaxf(bmax, st[i]);
;     bmax = fmaxf(bmax, __shfl_xor(bmax, 32));
;     const float mnew = fmaxf(mrun, bmax);
;     float lsum = 0.f;
; #pragma unroll
;     for (int i = 0; i < 16; ++i) { st[i] = __builtin_amdgcn_exp2f(st[i] - mnew); lsum += st[i]; }
;     lsum += __shfl_xor(lsum, 32);
;     const float alpha = __builtin_amdgcn_exp2f(mrun - mnew);
;     lrun = lrun * alpha + lsum; mrun = mnew;
; #pragma unroll
; __device__ __forceinline__ void att_phase(unsigned char* ws, LAS unsigned char* lds, int lane, int wave, int G) {
;     ...
;             asm volatile("s_waitcnt vmcnt(0)" ::: "memory");
;             if (kb < 5) ATT_DMA_KV(P, kb + 1, sb ^ 1);
;             else if (hn) ATT_DMA_KV(N, 0, sb ^ 1);
;             bf16x8 kf[4], va[4];
; #pragma unroll
;             for (int kk = 0; kk < 4; ++kk) kf[kk] = *(LAS const bf16x8*)(kfb + sb * 4096 + (((2 * kk + h) ^ (qc & 7)) << 4));
;             LAS const unsigned char* trs = trb + 8192 + sb * 4096;
; #pragma unroll
;             for (int s = 0; s < 2; ++s) {
;                 const s16x4 lo0 = vtr(trs + (16 * s) * VP), hi0 = vtr(trs + (16 * s + 8) * VP);
;                 const s16x4 lo1 = vtr(trs + (16 * s) * VP + 64), hi1 = vtr(trs + (16 * s + 8) * VP + 64);
;                 va[2 * s] = (bf16x8){lo0[0], lo0[1], lo0[2], lo0[3], hi0[0], hi0[1], hi0[2], hi0[3]};
;                 va[2 * s + 1] = (bf16x8){lo1[0], lo1[1], lo1[2], lo1[3], hi1[0], hi1[1], hi1[2], hi1[3]};
;             }
;             if (kb <= 4) {
;                 att_block(kf, qfA, va, oA0, oA1, mA, lA, kb == 0 || kb == 4 || kminA > 32 * kb, mloA - 4 * h - 32 * kb, qc + 128 - 4 * h - 32 * kb);
.LBB0_80:
	v_add_u32_e32 v0, 0xffffffa0, v191
	v_mul_lo_u32 v0, s56, v0
	v_add_u32_e32 v4, s11, v0
	v_max_i32_e32 v164, 0, v4
	s_add_i32 s57, s33, 0x1000
	s_lshl_b32 s6, s56, 3
	s_waitcnt vmcnt(0)
	v_lshl_add_u32 v2, v164, 7, v180
	s_mov_b32 m0, s57
	s_add_i32 s7, s33, 0x3000
	v_add_u32_e32 v4, s6, v4
	global_load_lds_dwordx4 v2, s[98:99]
	v_lshl_add_u32 v0, v164, 7, v182
	s_mov_b32 m0, s7
	v_max_i32_e32 v164, 0, v4
	global_load_lds_dwordx4 v0, s[100:101]
	v_readlane_b32 s15, v254, 28
	v_lshl_add_u32 v2, v164, 7, v180
	s_mov_b32 m0, s15
	v_readlane_b32 s15, v254, 29
	v_add_u32_e32 v4, s6, v4
	global_load_lds_dwordx4 v2, s[98:99]
	v_lshl_add_u32 v0, v164, 7, v182
	s_mov_b32 m0, s15
	v_max_i32_e32 v164, 0, v4
	global_load_lds_dwordx4 v0, s[100:101]
	s_add_i32 s15, s33, 0x1800
	v_lshl_add_u32 v2, v164, 7, v180
	s_mov_b32 m0, s15
	s_add_i32 s17, s33, 0x3800
	v_add_u32_e32 v51, s6, v4
	global_load_lds_dwordx4 v2, s[98:99]
	v_lshl_add_u32 v0, v164, 7, v182
	s_mov_b32 m0, s17
	v_max_i32_e32 v164, 0, v51
	global_load_lds_dwordx4 v0, s[100:101]
	s_add_i32 s21, s33, 0x1c00
	v_lshl_add_u32 v2, v164, 7, v180
	s_mov_b32 m0, s21
	v_readlane_b32 s59, v254, 30
	global_load_lds_dwordx4 v2, s[98:99]
	v_lshl_add_u32 v0, v164, 7, v182
	s_mov_b32 m0, s59
	v_max_i32_e32 v199, s58, v189
	global_load_lds_dwordx4 v0, s[100:101]
	ds_read_b128 v[0:3], v225
	ds_read_b128 v[16:19], v226
	s_waitcnt lgkmcnt(0)
	v_mfma_f32_32x32x16_bf16 v[0:15], v[0:3], v[128:131], 0
	ds_read_b128 v[20:23], v228
	s_mov_b32 s59, 0xff800000
	v_mfma_f32_32x32x16_bf16 v[0:15], v[16:19], v[124:127], v[0:15]
	ds_read_b128 v[16:19], v227
	ds_read_b64_tr_b16 v[34:35], v229 offset:8192
	ds_read_b64_tr_b16 v[36:37], v229 offset:9216
	ds_read_b64_tr_b16 v[40:41], v229 offset:9280
	ds_read_b64_tr_b16 v[38:39], v229 offset:8256
	ds_read_b64_tr_b16 v[42:43], v229 offset:10240
	ds_read_b64_tr_b16 v[44:45], v229 offset:11264
	ds_read_b64_tr_b16 v[48:49], v229 offset:11328
	ds_read_b64_tr_b16 v[46:47], v229 offset:10304
	s_waitcnt lgkmcnt(8)
	v_mfma_f32_32x32x16_bf16 v[0:15], v[16:19], v[120:123], v[0:15]
	v_sub_u32_e32 v16, v199, v193
	v_mov_b32_e32 v17, v214
	s_waitcnt lgkmcnt(0)
	s_nop 0
	v_mfma_f32_32x32x16_bf16 v[0:15], v[20:23], v[116:119], v[0:15]
	s_nop 6
	v_cmp_ge_i32_e32 vcc, 0, v16
	v_cmp_ge_i32_e64 s[24:25], 1, v16
	v_cmp_ge_i32_e64 s[26:27], 2, v16
	v_cmp_ge_i32_e64 s[28:29], 3, v16
	s_nop 0
	v_cndmask_b32_e32 v0, v211, v0, vcc
	v_cmp_ge_i32_e32 vcc, 8, v16
	v_cndmask_b32_e64 v1, v211, v1, s[24:25]
	v_cmp_ge_i32_e64 s[24:25], 9, v16
	v_cndmask_b32_e64 v2, v211, v2, s[26:27]
	v_cmp_ge_i32_e64 s[26:27], 10, v16
	v_cndmask_b32_e64 v3, v211, v3, s[28:29]
	v_cmp_ge_i32_e64 s[28:29], 11, v16
	v_cndmask_b32_e32 v4, v211, v4, vcc
	v_cmp_ge_i32_e32 vcc, 16, v16
	v_cndmask_b32_e64 v5, v211, v5, s[24:25]
	v_cmp_ge_i32_e64 s[24:25], 17, v16
	v_cndmask_b32_e64 v6, v211, v6, s[26:27]
	v_cmp_ge_i32_e64 s[26:27], 18, v16
	v_cndmask_b32_e64 v7, v211, v7, s[28:29]
	v_cmp_ge_i32_e64 s[28:29], 19, v16
	v_cndmask_b32_e32 v8, v211, v8, vcc
	v_cmp_ge_i32_e32 vcc, 24, v16
	v_cndmask_b32_e64 v9, v211, v9, s[24:25]
	v_cmp_ge_i32_e64 s[24:25], 25, v16
	v_cndmask_b32_e64 v10, v211, v10, s[26:27]
	v_cmp_ge_i32_e64 s[26:27], 26, v16
	v_cndmask_b32_e64 v11, v211, v11, s[28:29]
	v_cmp_ge_i32_e64 s[28:29], 27, v16
	v_cndmask_b32_e32 v56, v211, v12, vcc
	v_cndmask_b32_e64 v57, v211, v13, s[24:25]
	v_cndmask_b32_e64 v58, v211, v14, s[26:27]
	v_cndmask_b32_e64 v59, v211, v15, s[28:29]
	s_nop 0
	s_nop 0
	v_max3_f32 v12, v0, s59, v1
	v_max3_f32 v12, v12, v2, v3
	v_max3_f32 v12, v12, v4, v5
	v_max3_f32 v12, v12, v6, v7
	v_max3_f32 v12, v12, v8, v9
	v_xor_b32_e32 v13, 32, v206
	v_max3_f32 v12, v12, v10, v11
	v_cmp_lt_i32_e32 vcc, v13, v208
	v_max3_f32 v12, v12, v56, v57
	v_max3_f32 v12, v12, v58, v59
	v_cndmask_b32_e32 v13, v206, v13, vcc
	v_lshlrev_b32_e32 v201, 2, v13
	ds_bpermute_b32 v13, v201, v12
	s_mov_b32 s59, 0xf149f2ca
	s_waitcnt lgkmcnt(0)
	v_max3_f32 v50, v12, v13, s59
	v_sub_f32_e32 v0, v0, v50
	v_exp_f32_e32 v16, v0
	v_sub_f32_e32 v0, v1, v50
	v_exp_f32_e32 v17, v0
	v_sub_f32_e32 v1, v2, v50
	v_exp_f32_e32 v18, v1
	v_sub_f32_e32 v1, v3, v50
	v_exp_f32_e32 v19, v1
	v_sub_f32_e32 v1, v4, v50
	v_add_f32_e32 v0, 0, v16
	v_exp_f32_e32 v20, v1
	v_sub_f32_e32 v1, v5, v50
	v_add_f32_e32 v0, v17, v0
	v_exp_f32_e32 v21, v1
	v_sub_f32_e32 v1, v6, v50
	v_add_f32_e32 v0, v18, v0
	v_exp_f32_e32 v22, v1
	v_sub_f32_e32 v1, v7, v50
	v_add_f32_e32 v0, v19, v0
	v_exp_f32_e32 v23, v1
	v_sub_f32_e32 v1, v8, v50
	v_add_f32_e32 v0, v20, v0
	v_exp_f32_e32 v60, v1
	v_sub_f32_e32 v1, v9, v50
	v_add_f32_e32 v0, v21, v0
	v_exp_f32_e32 v61, v1
	v_add_f32_e32 v0, v22, v0
	v_add_f32_e32 v0, v23, v0
	v_add_f32_e32 v0, v60, v0
	v_add_f32_e32 v62, v61, v0
	v_sub_f32_e32 v1, v10, v50
	v_cvt_pk_bf16_f32 v52, v16, v17
	v_sub_f32_e32 v16, v56, v50
	v_mov_b32_e32 v0, 0
	v_exp_f32_e32 v63, v1
	v_sub_f32_e32 v64, v11, v50
	v_cvt_pk_bf16_f32 v53, v18, v19
	v_cvt_pk_bf16_f32 v54, v20, v21
	v_cvt_pk_bf16_f32 v55, v22, v23
	v_exp_f32_e32 v56, v16
	v_sub_f32_e32 v16, v57, v50
	v_mfma_f32_32x32x16_bf16 v[18:33], v[34:37], v[52:55], 0
	v_exp_f32_e32 v57, v16
	v_sub_f32_e32 v34, v58, v50
	v_exp_f32_e32 v64, v64
	v_cvt_pk_bf16_f32 v36, v56, v57
	s_nop 1
	v_exp_f32_e32 v1, v34
	v_sub_f32_e32 v34, v59, v50
	v_mfma_f32_32x32x16_bf16 v[2:17], v[38:41], v[52:55], 0
	v_exp_f32_e32 v38, v34
	v_add_f32_e32 v39, v63, v62
	v_add_f32_e32 v39, v64, v39
	v_cvt_pk_bf16_f32 v34, v60, v61
	v_cvt_pk_bf16_f32 v35, v63, v64
	v_cvt_pk_bf16_f32 v37, v1, v38
	v_add_f32_e32 v39, v56, v39
	v_add_f32_e32 v39, v57, v39
	v_mfma_f32_32x32x16_bf16 v[18:33], v[42:45], v[34:37], v[18:33]
	v_add_f32_e32 v1, v1, v39
	v_add_f32_e32 v1, v38, v1
	ds_bpermute_b32 v232, v201, v1
	v_mfma_f32_32x32x16_bf16 v[2:17], v[46:49], v[34:37], v[2:17]
	v_add_u32_e32 v38, s6, v51
	v_max_i32_e32 v164, 0, v38
	s_mov_b32 m0, s33
	s_waitcnt vmcnt(0)
; #define LAS __attribute__((address_space(3)))
; __device__ __forceinline__ void att_block(const bf16x8 (&kf)[4], const bf16x8 (&qf)[4], const bf16x8 (&va)[4], f32x16& o0, f32x16& o1, float& mrun, float& lrun, bool domask, int lo_, int hi_) {
;     f32x16 st;
; #pragma unroll
;     for (int i = 0; i < 16; ++i) st[i] = 0.f;
; #pragma unroll
;     for (int kk = 0; kk < 4; ++kk) st = __builtin_amdgcn_mfma_f32_32x32x16_bf16(kf[kk], qf[kk], st, 0, 0, 0);
;     if (domask) {
;         asm volatile("" : "+v"(lo_), "+v"(hi_));
; #pragma unroll
;         for (int i = 0; i < 16; ++i) { const int ci = (i & 3) + 8 * (i >> 2); st[i] = ((ci - lo_) | (hi_ - ci)) < 0 ? -INFINITY : st[i]; }
;     }
;     float bmax = -INFINITY;
; #pragma unroll
;     for (int i = 0; i < 16; ++i) bmax = fmaxf(bmax, st[i]);
;     bmax = fmaxf(bmax, __shfl_xor(bmax, 32));
;     const float mnew = fmaxf(mrun, bmax);
;     float lsum = 0.f;
; #pragma unroll
; __device__ __forceinline__ void att_phase(unsigned char* ws, LAS unsigned char* lds, int lane, int wave, int G) {
;     ...
;             if (kb < 5) ATT_DMA_KV(P, kb + 1, sb ^ 1);
;             else if (hn) ATT_DMA_KV(N, 0, sb ^ 1);
;             bf16x8 kf[4], va[4];
; #pragma unroll
;             for (int kk = 0; kk < 4; ++kk) kf[kk] = *(LAS const bf16x8*)(kfb + sb * 4096 + (((2 * kk + h) ^ (qc & 7)) << 4));
;             LAS const unsigned char* trs = trb + 8192 + sb * 4096;
; #pragma unroll
;             for (int s = 0; s < 2; ++s) {
;                 const s16x4 lo0 = vtr(trs + (16 * s) * VP), hi0 = vtr(trs + (16 * s + 8) * VP);
;                 const s16x4 lo1 = vtr(trs + (16 * s) * VP + 64), hi1 = vtr(trs + (16 * s + 8) * VP + 64);
;                 va[2 * s] = (bf16x8){lo0[0], lo0[1], lo0[2], lo0[3], hi0[0], hi0[1], hi0[2], hi0[3]};
;                 va[2 * s + 1] = (bf16x8){lo1[0], lo1[1], lo1[2], lo1[3], hi1[0], hi1[1], hi1[2], hi1[3]};
;             }
;             if (kb <= 4) {
;                 att_block(kf, qfA, va, oA0, oA1, mA, lA, kb == 0 || kb == 4 || kminA > 32 * kb, mloA - 4 * h - 32 * kb, qc + 128 - 4 * h - 32 * kb);
;                 if (kb == 4 && hn) ATT_LOAD_Q(qfA, N, 0);
;             }
;             if (kb >= 1) {
;                 att_block(kf, qfB, va, oB0, oB1, mB, lB, kb == 1 || kb == 5 || kminB > 32 * (kb - 1), mloB - 4 * h - 32 * (kb - 1), qc + 128 - 4 * h - 32 * (kb - 1));
	v_lshl_add_u32 v36, v164, 7, v180
	v_add_u32_e32 v38, s6, v38
	global_load_lds_dwordx4 v36, s[98:99]
	v_lshl_add_u32 v34, v164, 7, v182
	s_mov_b32 m0, s44
	v_max_i32_e32 v164, 0, v38
	global_load_lds_dwordx4 v34, s[100:101]
	v_lshl_add_u32 v36, v164, 7, v180
	s_mov_b32 m0, s66
	v_add_u32_e32 v38, s6, v38
	global_load_lds_dwordx4 v36, s[98:99]
	v_lshl_add_u32 v34, v164, 7, v182
	s_mov_b32 m0, s67
	v_max_i32_e32 v164, 0, v38
	global_load_lds_dwordx4 v34, s[100:101]
	v_lshl_add_u32 v36, v164, 7, v180
	s_mov_b32 m0, s48
	v_lshl_add_u32 v34, v164, 7, v182
	global_load_lds_dwordx4 v36, s[98:99]
	s_mov_b32 m0, s49
	v_readlane_b32 s59, v254, 27
	global_load_lds_dwordx4 v34, s[100:101]
	v_add_u32_e32 v34, s6, v38
	v_max_i32_e32 v164, 0, v34
	v_lshl_add_u32 v36, v164, 7, v180
	s_mov_b32 m0, s72
	v_lshl_add_u32 v34, v164, 7, v182
	global_load_lds_dwordx4 v36, s[98:99]
	s_mov_b32 m0, s59
	s_cmp_gt_i32 s58, 32
	global_load_lds_dwordx4 v34, s[100:101]
	ds_read_b128 v[68:71], v225 offset:4096
	ds_read_b128 v[64:67], v226 offset:4096
	s_waitcnt lgkmcnt(0)
	v_mfma_f32_32x32x16_bf16 v[34:49], v[68:71], v[128:131], 0
	ds_read_b128 v[60:63], v227 offset:4096
	ds_read_b128 v[56:59], v228 offset:4096
	ds_read_b64_tr_b16 v[52:53], v229 offset:12288
	ds_read_b64_tr_b16 v[54:55], v229 offset:13312
	ds_read_b64_tr_b16 v[94:95], v229 offset:13376
	ds_read_b64_tr_b16 v[92:93], v229 offset:12352
	ds_read_b64_tr_b16 v[88:89], v229 offset:14336
	ds_read_b64_tr_b16 v[90:91], v229 offset:15360
	ds_read_b64_tr_b16 v[86:87], v229 offset:15424
	ds_read_b64_tr_b16 v[84:85], v229 offset:14400
	v_mfma_f32_32x32x16_bf16 v[34:49], v[64:67], v[124:127], v[34:49]
	s_waitcnt lgkmcnt(9)
	v_mfma_f32_32x32x16_bf16 v[34:49], v[60:63], v[120:123], v[34:49]
	s_waitcnt lgkmcnt(8)
	v_mfma_f32_32x32x16_bf16 v[34:49], v[56:59], v[116:119], v[34:49]
	s_cbranch_scc0 .LBB0_82
	v_sub_u32_e32 v51, v199, v215
	v_mov_b32_e32 v72, v216
	s_nop 0
	s_nop 1
	v_cmp_ge_i32_e32 vcc, 0, v51
	v_cmp_ge_i32_e64 s[24:25], 1, v51
	v_cmp_ge_i32_e64 s[26:27], 2, v51
	v_cmp_ge_i32_e64 s[28:29], 3, v51
	s_nop 1
	v_cndmask_b32_e32 v34, v211, v34, vcc
	v_cmp_ge_i32_e32 vcc, 8, v51
	v_cndmask_b32_e64 v35, v211, v35, s[24:25]
	v_cmp_ge_i32_e64 s[24:25], 9, v51
	v_cndmask_b32_e64 v36, v211, v36, s[26:27]
	v_cmp_ge_i32_e64 s[26:27], 10, v51
	v_cndmask_b32_e64 v37, v211, v37, s[28:29]
	v_cmp_ge_i32_e64 s[28:29], 11, v51
	v_cndmask_b32_e32 v38, v211, v38, vcc
	v_cmp_ge_i32_e32 vcc, 16, v51
	v_cndmask_b32_e64 v39, v211, v39, s[24:25]
	v_cmp_ge_i32_e64 s[24:25], 17, v51
	v_cndmask_b32_e64 v40, v211, v40, s[26:27]
	v_cmp_ge_i32_e64 s[26:27], 18, v51
	v_cndmask_b32_e64 v41, v211, v41, s[28:29]
	v_cmp_ge_i32_e64 s[28:29], 19, v51
	v_cndmask_b32_e32 v42, v211, v42, vcc
	v_cmp_ge_i32_e32 vcc, 24, v51
	v_cndmask_b32_e64 v43, v211, v43, s[24:25]
	v_cmp_ge_i32_e64 s[24:25], 25, v51
	v_cndmask_b32_e64 v44, v211, v44, s[26:27]
	v_cmp_ge_i32_e64 s[26:27], 26, v51
	v_cndmask_b32_e64 v45, v211, v45, s[28:29]
	v_cmp_ge_i32_e64 s[28:29], 27, v51
	v_cndmask_b32_e32 v46, v211, v46, vcc
	v_cndmask_b32_e64 v47, v211, v47, s[24:25]
	v_cndmask_b32_e64 v48, v211, v48, s[26:27]
	v_cndmask_b32_e64 v49, v211, v49, s[28:29]
	s_nop 0
	s_nop 1
.LBB0_82:
	s_mov_b32 s59, 0xff800000
	s_nop 9
	v_max3_f32 v51, v34, s59, v35
	v_max3_f32 v51, v51, v36, v37
	v_max3_f32 v51, v51, v38, v39
	v_max3_f32 v51, v51, v40, v41
	v_max3_f32 v51, v51, v42, v43
	v_max3_f32 v51, v51, v44, v45
	v_max3_f32 v51, v51, v46, v47
	v_max3_f32 v51, v51, v48, v49
	ds_bpermute_b32 v72, v201, v51
	v_max_i32_e32 v237, s14, v189
	s_mov_b32 s60, 0xff800000
	s_waitcnt lgkmcnt(0)
	v_max3_f32 v148, v50, v51, v72
	v_sub_f32_e32 v34, v34, v148
	v_exp_f32_e32 v72, v34
	v_sub_f32_e32 v35, v35, v148
	v_exp_f32_e32 v73, v35
	v_sub_f32_e32 v35, v36, v148
	v_exp_f32_e32 v74, v35
	v_sub_f32_e32 v35, v37, v148
	v_exp_f32_e32 v75, v35
	v_sub_f32_e32 v35, v38, v148
	v_add_f32_e32 v34, 0, v72
	v_exp_f32_e32 v76, v35
	v_sub_f32_e32 v35, v39, v148
	v_add_f32_e32 v34, v73, v34
	v_exp_f32_e32 v77, v35
	v_sub_f32_e32 v35, v40, v148
	v_add_f32_e32 v34, v74, v34
	v_exp_f32_e32 v78, v35
	v_sub_f32_e32 v35, v41, v148
	v_add_f32_e32 v34, v75, v34
	v_exp_f32_e32 v79, v35
	v_sub_f32_e32 v35, v42, v148
	v_add_f32_e32 v34, v76, v34
	v_exp_f32_e32 v80, v35
	v_sub_f32_e32 v35, v43, v148
	v_add_f32_e32 v34, v77, v34
	v_exp_f32_e32 v81, v35
	v_sub_f32_e32 v35, v44, v148
	v_add_f32_e32 v34, v78, v34
	v_exp_f32_e32 v82, v35
	v_sub_f32_e32 v35, v45, v148
	v_add_f32_e32 v34, v79, v34
	v_exp_f32_e32 v83, v35
	v_sub_f32_e32 v35, v46, v148
	v_add_f32_e32 v34, v80, v34
	v_exp_f32_e32 v96, v35
	v_sub_f32_e32 v35, v47, v148
	v_add_f32_e32 v34, v81, v34
	v_exp_f32_e32 v97, v35
	v_sub_f32_e32 v35, v48, v148
	v_add_f32_e32 v34, v82, v34
	v_exp_f32_e32 v98, v35
	v_sub_f32_e32 v35, v49, v148
	v_add_f32_e32 v34, v83, v34
	v_exp_f32_e32 v99, v35
	v_add_f32_e32 v34, v96, v34
	v_add_f32_e32 v34, v97, v34
	v_add_f32_e32 v34, v98, v34
	v_add_f32_e32 v235, v99, v34
	v_sub_f32_e32 v34, v50, v148
	v_exp_f32_e32 v188, v34
	ds_bpermute_b32 v236, v201, v235
	v_pk_mul_f32 v[34:35], v[32:33], v[188:189] op_sel_hi:[1,0]
	v_pk_mul_f32 v[32:33], v[30:31], v[188:189] op_sel_hi:[1,0]
	v_pk_mul_f32 v[30:31], v[28:29], v[188:189] op_sel_hi:[1,0]
	v_pk_mul_f32 v[28:29], v[26:27], v[188:189] op_sel_hi:[1,0]
	v_pk_mul_f32 v[26:27], v[24:25], v[188:189] op_sel_hi:[1,0]
	v_pk_mul_f32 v[24:25], v[22:23], v[188:189] op_sel_hi:[1,0]
	v_pk_mul_f32 v[22:23], v[20:21], v[188:189] op_sel_hi:[1,0]
	v_pk_mul_f32 v[20:21], v[18:19], v[188:189] op_sel_hi:[1,0]
	v_pk_mul_f32 v[50:51], v[16:17], v[188:189] op_sel_hi:[1,0]
	v_pk_mul_f32 v[48:49], v[14:15], v[188:189] op_sel_hi:[1,0]
	v_pk_mul_f32 v[46:47], v[12:13], v[188:189] op_sel_hi:[1,0]
	v_pk_mul_f32 v[44:45], v[10:11], v[188:189] op_sel_hi:[1,0]
	v_pk_mul_f32 v[42:43], v[8:9], v[188:189] op_sel_hi:[1,0]
	v_pk_mul_f32 v[40:41], v[6:7], v[188:189] op_sel_hi:[1,0]
	v_pk_mul_f32 v[38:39], v[4:5], v[188:189] op_sel_hi:[1,0]
	v_pk_mul_f32 v[36:37], v[2:3], v[188:189] op_sel_hi:[1,0]
	v_cvt_pk_bf16_f32 v2, v72, v73
	v_cvt_pk_bf16_f32 v3, v74, v75
	v_cvt_pk_bf16_f32 v4, v76, v77
	v_cvt_pk_bf16_f32 v5, v78, v79
	v_sub_u32_e32 v18, v237, v193
	v_mov_b32_e32 v19, v214
	v_mfma_f32_32x32x16_bf16 v[20:35], v[52:55], v[2:5], v[20:35]
	s_waitcnt lgkmcnt(0)
; __device__ __forceinline__ unsigned pk2(float lo, float hi) { return pg8::cvt_pk_bf16(lo, hi); }
; __device__ __forceinline__ void att_block(const bf16x8 (&kf)[4], const bf16x8 (&qf)[4], const bf16x8 (&va)[4], f32x16& o0, f32x16& o1, float& mrun, float& lrun, bool domask, int lo_, int hi_) {
;     f32x16 st;
; #pragma unroll
;     for (int i = 0; i < 16; ++i) st[i] = 0.f;
; #pragma unroll
;     for (int kk = 0; kk < 4; ++kk) st = __builtin_amdgcn_mfma_f32_32x32x16_bf16(kf[kk], qf[kk], st, 0, 0, 0);
;     if (domask) {
;         asm volatile("" : "+v"(lo_), "+v"(hi_));
; #pragma unroll
;         for (int i = 0; i < 16; ++i) { const int ci = (i & 3) + 8 * (i >> 2); st[i] = ((ci - lo_) | (hi_ - ci)) < 0 ? -INFINITY : st[i]; }
;     }
;     float bmax = -INFINITY;
; #pragma unroll
;     for (int i = 0; i < 16; ++i) bmax = fmaxf(bmax, st[i]);
;     bmax = fmaxf(bmax, __shfl_xor(bmax, 32));
;     const float mnew = fmaxf(mrun, bmax);
;     float lsum = 0.f;
; #pragma unroll
;     for (int i = 0; i < 16; ++i) { st[i] = __builtin_amdgcn_exp2f(st[i] - mnew); lsum += st[i]; }
;     lsum += __shfl_xor(lsum, 32);
;     const float alpha = __builtin_amdgcn_exp2f(mrun - mnew);
;     lrun = lrun * alpha + lsum; mrun = mnew;
; #pragma unroll
;     for (int i = 0; i < 16; ++i) { o0[i] *= alpha; o1[i] *= alpha; }
; #pragma unroll
;     for (int s = 0; s < 2; ++s) { v4u w; w.x = pk2(st[8 * s], st[8 * s + 1]); w.y = pk2(st[8 * s + 2], st[8 * s + 3]); w.z = pk2(st[8 * s + 4], st[8 * s + 5]); w.w = pk2(st[8 * s + 6], st[8 * s + 7]);
;         const bf16x8 pb = __builtin_bit_cast(bf16x8, w);
;         o0 = __builtin_amdgcn_mfma_f32_32x32x16_bf16(va[2 * s], pb, o0, 0, 0, 0);
;         o1 = __builtin_amdgcn_mfma_f32_32x32x16_bf16(va[2 * s + 1], pb, o1, 0, 0, 0); }
; __device__ __forceinline__ void att_phase(unsigned char* ws, LAS unsigned char* lds, int lane, int wave, int G) {
;     ...
;             if (kb <= 4) {
;                 att_block(kf, qfA, va, oA0, oA1, mA, lA, kb == 0 || kb == 4 || kminA > 32 * kb, mloA - 4 * h - 32 * kb, qc + 128 - 4 * h - 32 * kb);
;                 if (kb == 4 && hn) ATT_LOAD_Q(qfA, N, 0);
;             }
;             if (kb >= 1) {
;                 att_block(kf, qfB, va, oB0, oB1, mB, lB, kb == 1 || kb == 5 || kminB > 32 * (kb - 1), mloB - 4 * h - 32 * (kb - 1), qc + 128 - 4 * h - 32 * (kb - 1));
	v_mfma_f32_32x32x16_bf16 v[36:51], v[92:95], v[2:5], v[36:51]
	v_cvt_pk_bf16_f32 v2, v80, v81
	v_cvt_pk_bf16_f32 v3, v82, v83
	v_cvt_pk_bf16_f32 v4, v96, v97
	v_cvt_pk_bf16_f32 v5, v98, v99
	s_nop 1
	v_mfma_f32_32x32x16_bf16 v[20:35], v[88:91], v[2:5], v[20:35]
	v_mfma_f32_32x32x16_bf16 v[36:51], v[84:87], v[2:5], v[36:51]
	v_mfma_f32_32x32x16_bf16 v[2:17], v[68:71], v[112:115], 0
	v_mfma_f32_32x32x16_bf16 v[2:17], v[64:67], v[108:111], v[2:17]
	v_mfma_f32_32x32x16_bf16 v[2:17], v[60:63], v[104:107], v[2:17]
	v_mfma_f32_32x32x16_bf16 v[2:17], v[56:59], v[100:103], v[2:17]
	s_nop 4
	v_cmp_ge_i32_e32 vcc, 0, v18
	v_cmp_ge_i32_e64 s[24:25], 1, v18
	v_cmp_ge_i32_e64 s[26:27], 2, v18
	v_cmp_ge_i32_e64 s[28:29], 3, v18
	s_nop 2
	v_cndmask_b32_e32 v2, v211, v2, vcc
	v_cmp_ge_i32_e32 vcc, 8, v18
	v_cndmask_b32_e64 v3, v211, v3, s[24:25]
	v_cmp_ge_i32_e64 s[24:25], 9, v18
	v_cndmask_b32_e64 v4, v211, v4, s[26:27]
	v_cmp_ge_i32_e64 s[26:27], 10, v18
	v_cndmask_b32_e64 v5, v211, v5, s[28:29]
	v_cmp_ge_i32_e64 s[28:29], 11, v18
	v_cndmask_b32_e32 v6, v211, v6, vcc
	v_cmp_ge_i32_e32 vcc, 16, v18
	v_cndmask_b32_e64 v7, v211, v7, s[24:25]
	v_cmp_ge_i32_e64 s[24:25], 17, v18
	v_cndmask_b32_e64 v8, v211, v8, s[26:27]
	v_cmp_ge_i32_e64 s[26:27], 18, v18
	v_cndmask_b32_e64 v9, v211, v9, s[28:29]
	v_cmp_ge_i32_e64 s[28:29], 19, v18
	v_cndmask_b32_e32 v10, v211, v10, vcc
	v_cmp_ge_i32_e32 vcc, 24, v18
	v_cndmask_b32_e64 v11, v211, v11, s[24:25]
	v_cmp_ge_i32_e64 s[24:25], 25, v18
	v_cndmask_b32_e64 v12, v211, v12, s[26:27]
	v_cmp_ge_i32_e64 s[26:27], 26, v18
	v_cndmask_b32_e64 v13, v211, v13, s[28:29]
	v_cmp_ge_i32_e64 s[28:29], 27, v18
	v_cndmask_b32_e32 v14, v211, v14, vcc
	v_cndmask_b32_e64 v15, v211, v15, s[24:25]
	v_cndmask_b32_e64 v16, v211, v16, s[26:27]
	v_cndmask_b32_e64 v17, v211, v17, s[28:29]
	s_nop 0
	v_max3_f32 v18, v2, s59, v3
	v_max3_f32 v18, v18, v4, v5
	v_max3_f32 v18, v18, v6, v7
	v_max3_f32 v18, v18, v8, v9
	v_max3_f32 v18, v18, v10, v11
	v_max3_f32 v18, v18, v12, v13
	v_max3_f32 v18, v18, v14, v15
	v_max3_f32 v18, v18, v16, v17
	ds_bpermute_b32 v19, v201, v18
	s_mov_b32 s59, 0xf149f2ca
	s_waitcnt lgkmcnt(0)
	v_max3_f32 v150, v18, v19, s59
	v_sub_f32_e32 v2, v2, v150
	v_exp_f32_e32 v18, v2
	v_sub_f32_e32 v3, v3, v150
	v_exp_f32_e32 v19, v3
	v_sub_f32_e32 v3, v4, v150
	v_exp_f32_e32 v56, v3
	v_sub_f32_e32 v3, v5, v150
	v_exp_f32_e32 v57, v3
	v_sub_f32_e32 v3, v6, v150
	v_add_f32_e32 v2, 0, v18
	v_exp_f32_e32 v58, v3
	v_sub_f32_e32 v3, v7, v150
	v_add_f32_e32 v2, v19, v2
	v_exp_f32_e32 v59, v3
	v_sub_f32_e32 v3, v8, v150
	v_add_f32_e32 v2, v56, v2
	v_exp_f32_e32 v60, v3
	v_sub_f32_e32 v3, v9, v150
	v_add_f32_e32 v2, v57, v2
	v_exp_f32_e32 v61, v3
	v_sub_f32_e32 v3, v10, v150
	v_add_f32_e32 v2, v58, v2
	v_exp_f32_e32 v132, v3
	v_sub_f32_e32 v3, v11, v150
	v_add_f32_e32 v2, v59, v2
	v_exp_f32_e32 v133, v3
	v_sub_f32_e32 v3, v12, v150
	v_add_f32_e32 v2, v60, v2
	v_exp_f32_e32 v134, v3
	v_sub_f32_e32 v3, v13, v150
	v_add_f32_e32 v2, v61, v2
	v_exp_f32_e32 v135, v3
	v_sub_f32_e32 v3, v14, v150
	v_add_f32_e32 v2, v132, v2
	v_exp_f32_e32 v136, v3
	v_sub_f32_e32 v3, v15, v150
	v_add_f32_e32 v2, v133, v2
	v_exp_f32_e32 v137, v3
	v_sub_f32_e32 v3, v16, v150
	v_add_f32_e32 v2, v134, v2
	v_exp_f32_e32 v138, v3
	v_sub_f32_e32 v3, v17, v150
	v_add_f32_e32 v2, v135, v2
	v_exp_f32_e32 v139, v3
	v_add_f32_e32 v2, v136, v2
	v_add_f32_e32 v2, v137, v2
	v_add_f32_e32 v2, v138, v2
	v_add_f32_e32 v233, v139, v2
	v_cvt_pk_bf16_f32 v96, v18, v19
	v_cvt_pk_bf16_f32 v97, v56, v57
	v_cvt_pk_bf16_f32 v98, v58, v59
	v_mov_b32_e32 v2, 0
	v_cvt_pk_bf16_f32 v99, v60, v61
	ds_bpermute_b32 v234, v201, v233
	s_nop 0
	v_mfma_f32_32x32x16_bf16 v[68:83], v[52:55], v[96:99], 0
	v_cvt_pk_bf16_f32 v4, v132, v133
	v_cvt_pk_bf16_f32 v5, v134, v135
	v_mfma_f32_32x32x16_bf16 v[52:67], v[92:95], v[96:99], 0
	v_cvt_pk_bf16_f32 v6, v136, v137
	v_cvt_pk_bf16_f32 v7, v138, v139
	s_nop 1
	v_mfma_f32_32x32x16_bf16 v[68:83], v[88:91], v[4:7], v[68:83]
	v_mfma_f32_32x32x16_bf16 v[52:67], v[84:87], v[4:7], v[52:67]
	v_mul_lo_u32 v3, s56, v217
	v_add_u32_e32 v3, s11, v3
	v_max_i32_e32 v164, 0, v3
	s_mov_b32 m0, s57
	s_waitcnt vmcnt(0)
	v_lshl_add_u32 v6, v164, 7, v180
	v_add_u32_e32 v3, s6, v3
	global_load_lds_dwordx4 v6, s[98:99]
	v_lshl_add_u32 v4, v164, 7, v182
	s_mov_b32 m0, s7
	v_max_i32_e32 v164, 0, v3
	global_load_lds_dwordx4 v4, s[100:101]
	v_readlane_b32 s59, v254, 28
	v_lshl_add_u32 v6, v164, 7, v180
	s_mov_b32 m0, s59
	v_readlane_b32 s59, v254, 29
	v_add_u32_e32 v3, s6, v3
	global_load_lds_dwordx4 v6, s[98:99]
	v_lshl_add_u32 v4, v164, 7, v182
	s_mov_b32 m0, s59
	v_max_i32_e32 v164, 0, v3
	global_load_lds_dwordx4 v4, s[100:101]
	v_lshl_add_u32 v6, v164, 7, v180
	s_mov_b32 m0, s15
	v_add_u32_e32 v3, s6, v3
	global_load_lds_dwordx4 v6, s[98:99]
	v_lshl_add_u32 v4, v164, 7, v182
	s_mov_b32 m0, s17
	v_max_i32_e32 v164, 0, v3
	global_load_lds_dwordx4 v4, s[100:101]
	v_lshl_add_u32 v6, v164, 7, v180
	s_mov_b32 m0, s21
	v_readlane_b32 s59, v254, 30
	global_load_lds_dwordx4 v6, s[98:99]
	v_lshl_add_u32 v4, v164, 7, v182
	s_mov_b32 m0, s59
	s_cmpk_lt_i32 s58, 0x41
	global_load_lds_dwordx4 v4, s[100:101]
	ds_read_b128 v[144:147], v225
	ds_read_b128 v[140:143], v226
	s_waitcnt lgkmcnt(0)
	v_mfma_f32_32x32x16_bf16 v[4:19], v[144:147], v[128:131], 0
	ds_read_b128 v[136:139], v227
	ds_read_b128 v[132:135], v228
	ds_read_b64_tr_b16 v[96:97], v229 offset:8192
	ds_read_b64_tr_b16 v[98:99], v229 offset:9216
	ds_read_b64_tr_b16 v[94:95], v229 offset:9280
	ds_read_b64_tr_b16 v[92:93], v229 offset:8256
	ds_read_b64_tr_b16 v[88:89], v229 offset:10240
	ds_read_b64_tr_b16 v[90:91], v229 offset:11264
	ds_read_b64_tr_b16 v[86:87], v229 offset:11328
	ds_read_b64_tr_b16 v[84:85], v229 offset:10304
	v_mfma_f32_32x32x16_bf16 v[4:19], v[140:143], v[124:127], v[4:19]
	s_waitcnt lgkmcnt(9)
	v_mfma_f32_32x32x16_bf16 v[4:19], v[136:139], v[120:123], v[4:19]
	s_waitcnt lgkmcnt(8)
	v_mfma_f32_32x32x16_bf16 v[4:19], v[132:135], v[116:119], v[4:19]
	s_cbranch_scc1 .LBB0_84
; __device__ __forceinline__ void att_block(const bf16x8 (&kf)[4], const bf16x8 (&qf)[4], const bf16x8 (&va)[4], f32x16& o0, f32x16& o1, float& mrun, float& lrun, bool domask, int lo_, int hi_) {
;     ...
;     if (domask) {
;         asm volatile("" : "+v"(lo_), "+v"(hi_));
; #pragma unroll
;         for (int i = 0; i < 16; ++i) { const int ci = (i & 3) + 8 * (i >> 2); st[i] = ((ci - lo_) | (hi_ - ci)) < 0 ? -INFINITY : st[i]; }
;     }
	v_sub_u32_e32 v3, v199, v218
	v_mov_b32_e32 v149, v219
	s_nop 0
	s_nop 1
	v_cmp_ge_i32_e32 vcc, 0, v3
	v_cmp_ge_i32_e64 s[24:25], 1, v3
	v_cmp_ge_i32_e64 s[26:27], 2, v3
	v_cmp_ge_i32_e64 s[28:29], 3, v3
	s_nop 1
	v_cndmask_b32_e32 v4, v211, v4, vcc
	v_cmp_ge_i32_e32 vcc, 8, v3
	v_cndmask_b32_e64 v5, v211, v5, s[24:25]
	v_cmp_ge_i32_e64 s[24:25], 9, v3
	v_cndmask_b32_e64 v6, v211, v6, s[26:27]
	v_cmp_ge_i32_e64 s[26:27], 10, v3
	v_cndmask_b32_e64 v7, v211, v7, s[28:29]
	v_cmp_ge_i32_e64 s[28:29], 11, v3
	v_cndmask_b32_e32 v8, v211, v8, vcc
	v_cmp_ge_i32_e32 vcc, 16, v3
	v_cndmask_b32_e64 v9, v211, v9, s[24:25]
	v_cmp_ge_i32_e64 s[24:25], 17, v3
	v_cndmask_b32_e64 v10, v211, v10, s[26:27]
	v_cmp_ge_i32_e64 s[26:27], 18, v3
	v_cndmask_b32_e64 v11, v211, v11, s[28:29]
	v_cmp_ge_i32_e64 s[28:29], 19, v3
	v_cndmask_b32_e32 v12, v211, v12, vcc
	v_cmp_ge_i32_e32 vcc, 24, v3
	v_cndmask_b32_e64 v13, v211, v13, s[24:25]
	v_cmp_ge_i32_e64 s[24:25], 25, v3
	v_cndmask_b32_e64 v14, v211, v14, s[26:27]
	v_cmp_ge_i32_e64 s[26:27], 26, v3
	v_cndmask_b32_e64 v15, v211, v15, s[28:29]
	v_cmp_ge_i32_e64 s[28:29], 27, v3
	v_cndmask_b32_e32 v16, v211, v16, vcc
	v_cndmask_b32_e64 v17, v211, v17, s[24:25]
	v_cndmask_b32_e64 v18, v211, v18, s[26:27]
	v_cndmask_b32_e64 v19, v211, v19, s[28:29]
	s_nop 0
	s_nop 1

; __device__ __forceinline__ void att_block(const bf16x8 (&kf)[4], const bf16x8 (&qf)[4], const bf16x8 (&va)[4], f32x16& o0, f32x16& o1, float& mrun, float& lrun, bool domask, int lo_, int hi_) {
;     f32x16 st;
; #pragma unroll
;     for (int i = 0; i < 16; ++i) st[i] = 0.f;
; #pragma unroll
;     for (int kk = 0; kk < 4; ++kk) st = __builtin_amdgcn_mfma_f32_32x32x16_bf16(kf[kk], qf[kk], st, 0, 0, 0);
;     if (domask) {
;         asm volatile("" : "+v"(lo_), "+v"(hi_));
; #pragma unroll
;         for (int i = 0; i < 16; ++i) { const int ci = (i & 3) + 8 * (i >> 2); st[i] = ((ci - lo_) | (hi_ - ci)) < 0 ? -INFINITY : st[i]; }
;     }
;     float bmax = -INFINITY;
; #pragma unroll
;     for (int i = 0; i < 16; ++i) bmax = fmaxf(bmax, st[i]);
;     bmax = fmaxf(bmax, __shfl_xor(bmax, 32));
;     const float mnew = fmaxf(mrun, bmax);
;     float lsum = 0.f;
; #pragma unroll
;     for (int i = 0; i < 16; ++i) { st[i] = __builtin_amdgcn_exp2f(st[i] - mnew); lsum += st[i]; }
;     lsum += __shfl_xor(lsum, 32);
;     const float alpha = __builtin_amdgcn_exp2f(mrun - mnew);
;     lrun = lrun * alpha + lsum; mrun = mnew;
; #pragma unroll
;     for (int i = 0; i < 16; ++i) { o0[i] *= alpha; o1[i] *= alpha; }
; #pragma unroll
;     for (int s = 0; s < 2; ++s) { v4u w; w.x = pk2(st[8 * s], st[8 * s + 1]); w.y = pk2(st[8 * s + 2], st[8 * s + 3]); w.z = pk2(st[8 * s + 4], st[8 * s + 5]); w.w = pk2(st[8 * s + 6], st[8 * s + 7]);
;         const bf16x8 pb = __builtin_bit_cast(bf16x8, w);
;         o0 = __builtin_amdgcn_mfma_f32_32x32x16_bf16(va[2 * s], pb, o0, 0, 0, 0);
;         o1 = __builtin_amdgcn_mfma_f32_32x32x16_bf16(va[2 * s + 1], pb, o1, 0, 0, 0); }
; __device__ __forceinline__ void att_phase(unsigned char* ws, LAS unsigned char* lds, int lane, int wave, int G) {
;     ...
;             asm volatile("s_waitcnt vmcnt(0)" ::: "memory");
;             if (kb < 5) ATT_DMA_KV(P, kb + 1, sb ^ 1);
;             else if (hn) ATT_DMA_KV(N, 0, sb ^ 1);
;             bf16x8 kf[4], va[4];
; #pragma unroll
;             for (int kk = 0; kk < 4; ++kk) kf[kk] = *(LAS const bf16x8*)(kfb + sb * 4096 + (((2 * kk + h) ^ (qc & 7)) << 4));
;             LAS const unsigned char* trs = trb + 8192 + sb * 4096;
; #pragma unroll
;             for (int s = 0; s < 2; ++s) {
;                 const s16x4 lo0 = vtr(trs + (16 * s) * VP), hi0 = vtr(trs + (16 * s + 8) * VP);
.LBB0_86:
	s_nop 10
	v_max3_f32 v3, v36, s60, v37
	v_max3_f32 v3, v3, v38, v39
	v_max3_f32 v3, v3, v40, v41
	v_max3_f32 v3, v3, v42, v43
	v_max3_f32 v3, v3, v44, v45
	v_max3_f32 v3, v3, v46, v47
	v_max3_f32 v3, v3, v48, v49
	v_max3_f32 v3, v3, v50, v51
	ds_bpermute_b32 v132, v201, v3
	s_waitcnt lgkmcnt(0)
	s_waitcnt lgkmcnt(0)
	v_max3_f32 v148, v150, v3, v132
	v_sub_f32_e32 v3, v36, v148
	v_sub_f32_e32 v36, v37, v148
	v_exp_f32_e32 v133, v36
	v_sub_f32_e32 v36, v38, v148
	v_exp_f32_e32 v134, v36
	v_sub_f32_e32 v36, v39, v148
	v_exp_f32_e32 v135, v36
	v_sub_f32_e32 v36, v40, v148
	v_exp_f32_e32 v136, v36
	v_sub_f32_e32 v36, v41, v148
	v_exp_f32_e32 v137, v36
	v_sub_f32_e32 v36, v42, v148
	v_exp_f32_e32 v138, v36
	v_sub_f32_e32 v36, v43, v148
	v_exp_f32_e32 v139, v36
	v_sub_f32_e32 v36, v44, v148
	v_exp_f32_e32 v140, v36
	v_sub_f32_e32 v36, v45, v148
	v_exp_f32_e32 v141, v36
	v_sub_f32_e32 v36, v46, v148
	v_exp_f32_e32 v142, v36
	v_sub_f32_e32 v36, v47, v148
	v_exp_f32_e32 v143, v36
	v_sub_f32_e32 v36, v48, v148
	v_exp_f32_e32 v132, v3
	v_exp_f32_e32 v144, v36
	v_sub_f32_e32 v36, v49, v148
	v_exp_f32_e32 v145, v36
	v_sub_f32_e32 v36, v50, v148
	v_exp_f32_e32 v146, v36
	v_sub_f32_e32 v36, v51, v148
	v_exp_f32_e32 v147, v36
	v_sub_f32_e32 v36, v150, v148
	v_add_f32_e32 v3, 0, v132
	v_exp_f32_e32 v190, v36
	v_add_f32_e32 v3, v133, v3
	v_add_f32_e32 v3, v134, v3
	v_add_f32_e32 v3, v135, v3
	v_add_f32_e32 v3, v136, v3
	v_pk_mul_f32 v[50:51], v[82:83], v[190:191] op_sel_hi:[1,0]
	v_pk_mul_f32 v[48:49], v[80:81], v[190:191] op_sel_hi:[1,0]
	v_pk_mul_f32 v[46:47], v[78:79], v[190:191] op_sel_hi:[1,0]
	v_pk_mul_f32 v[44:45], v[76:77], v[190:191] op_sel_hi:[1,0]
	v_pk_mul_f32 v[42:43], v[74:75], v[190:191] op_sel_hi:[1,0]
	v_pk_mul_f32 v[40:41], v[72:73], v[190:191] op_sel_hi:[1,0]
	v_pk_mul_f32 v[38:39], v[70:71], v[190:191] op_sel_hi:[1,0]
	v_pk_mul_f32 v[36:37], v[68:69], v[190:191] op_sel_hi:[1,0]
	v_pk_mul_f32 v[66:67], v[66:67], v[190:191] op_sel_hi:[1,0]
	v_pk_mul_f32 v[64:65], v[64:65], v[190:191] op_sel_hi:[1,0]
	v_pk_mul_f32 v[62:63], v[62:63], v[190:191] op_sel_hi:[1,0]
	v_pk_mul_f32 v[60:61], v[60:61], v[190:191] op_sel_hi:[1,0]
	v_pk_mul_f32 v[58:59], v[58:59], v[190:191] op_sel_hi:[1,0]
	v_pk_mul_f32 v[56:57], v[56:57], v[190:191] op_sel_hi:[1,0]
	v_pk_mul_f32 v[54:55], v[54:55], v[190:191] op_sel_hi:[1,0]
	v_pk_mul_f32 v[52:53], v[52:53], v[190:191] op_sel_hi:[1,0]
	v_cvt_pk_bf16_f32 v68, v132, v133
	v_cvt_pk_bf16_f32 v69, v134, v135
	v_cvt_pk_bf16_f32 v70, v136, v137
	v_cvt_pk_bf16_f32 v71, v138, v139
	v_add_f32_e32 v3, v137, v3
	v_add_f32_e32 v3, v138, v3
	v_mfma_f32_32x32x16_bf16 v[36:51], v[96:99], v[68:71], v[36:51]
	v_add_f32_e32 v3, v139, v3
	v_add_f32_e32 v3, v140, v3
	v_add_f32_e32 v3, v141, v3
	v_add_f32_e32 v3, v142, v3
	v_add_f32_e32 v3, v143, v3
	v_add_f32_e32 v3, v144, v3
	v_add_f32_e32 v3, v145, v3
	v_mfma_f32_32x32x16_bf16 v[52:67], v[92:95], v[68:71], v[52:67]
	v_cvt_pk_bf16_f32 v68, v140, v141
	v_cvt_pk_bf16_f32 v69, v142, v143
	v_cvt_pk_bf16_f32 v70, v144, v145
	v_cvt_pk_bf16_f32 v71, v146, v147
	v_add_f32_e32 v3, v146, v3
	v_add_f32_e32 v3, v147, v3
	ds_bpermute_b32 v238, v201, v3
	v_mfma_f32_32x32x16_bf16 v[36:51], v[88:91], v[68:71], v[36:51]
	v_mfma_f32_32x32x16_bf16 v[52:67], v[84:87], v[68:71], v[52:67]
	v_mul_lo_u32 v68, s56, v191
	v_add_u32_e32 v72, s11, v68
	v_max_i32_e32 v164, 0, v72
	s_mov_b32 m0, s33
	s_waitcnt vmcnt(0)
	v_lshl_add_u32 v70, v164, 7, v180
	v_add_u32_e32 v72, s6, v72
	global_load_lds_dwordx4 v70, s[98:99]
	v_lshl_add_u32 v68, v164, 7, v182
	s_mov_b32 m0, s44
	v_max_i32_e32 v164, 0, v72
	global_load_lds_dwordx4 v68, s[100:101]
	v_lshl_add_u32 v70, v164, 7, v180
	s_mov_b32 m0, s66
	v_add_u32_e32 v72, s6, v72
	global_load_lds_dwordx4 v70, s[98:99]
	v_lshl_add_u32 v68, v164, 7, v182
	s_mov_b32 m0, s67
	v_max_i32_e32 v164, 0, v72
	global_load_lds_dwordx4 v68, s[100:101]
	v_lshl_add_u32 v70, v164, 7, v180
	s_mov_b32 m0, s48
	v_lshl_add_u32 v68, v164, 7, v182
	global_load_lds_dwordx4 v70, s[98:99]
	s_mov_b32 m0, s49
	v_readlane_b32 s59, v254, 27
	global_load_lds_dwordx4 v68, s[100:101]
	v_add_u32_e32 v68, s6, v72
	v_max_i32_e32 v164, 0, v68
	v_lshl_add_u32 v70, v164, 7, v180
	s_mov_b32 m0, s72
	v_lshl_add_u32 v68, v164, 7, v182
	global_load_lds_dwordx4 v70, s[98:99]
	s_mov_b32 m0, s59
	s_cmpk_lt_i32 s58, 0x61
	global_load_lds_dwordx4 v68, s[100:101]
	ds_read_b128 v[96:99], v225 offset:4096
	ds_read_b128 v[92:95], v226 offset:4096
	s_waitcnt lgkmcnt(0)
	v_mfma_f32_32x32x16_bf16 v[68:83], v[96:99], v[128:131], 0
	ds_read_b128 v[88:91], v227 offset:4096
	ds_read_b128 v[84:87], v228 offset:4096
	ds_read_b64_tr_b16 v[144:145], v229 offset:12288
	ds_read_b64_tr_b16 v[146:147], v229 offset:13312
	ds_read_b64_tr_b16 v[142:143], v229 offset:13376
	ds_read_b64_tr_b16 v[140:141], v229 offset:12352
	ds_read_b64_tr_b16 v[136:137], v229 offset:14336
	ds_read_b64_tr_b16 v[138:139], v229 offset:15360
	ds_read_b64_tr_b16 v[134:135], v229 offset:15424
	ds_read_b64_tr_b16 v[132:133], v229 offset:14400
	v_mfma_f32_32x32x16_bf16 v[68:83], v[92:95], v[124:127], v[68:83]
	s_waitcnt lgkmcnt(9)
	v_mfma_f32_32x32x16_bf16 v[68:83], v[88:91], v[120:123], v[68:83]
	s_waitcnt lgkmcnt(8)
	v_mfma_f32_32x32x16_bf16 v[68:83], v[84:87], v[116:119], v[68:83]
	s_cbranch_scc1 .LBB0_88
	v_sub_u32_e32 v150, v199, v220
	v_mov_b32_e32 v151, v221
	s_nop 0
	s_nop 1
	v_cmp_ge_i32_e32 vcc, 0, v150
	v_cmp_ge_i32_e64 s[24:25], 1, v150
	v_cmp_ge_i32_e64 s[26:27], 2, v150
	v_cmp_ge_i32_e64 s[28:29], 3, v150
	s_nop 1
	v_cndmask_b32_e32 v68, v211, v68, vcc
	v_cmp_ge_i32_e32 vcc, 8, v150
	v_cndmask_b32_e64 v69, v211, v69, s[24:25]
	v_cmp_ge_i32_e64 s[24:25], 9, v150
	v_cndmask_b32_e64 v70, v211, v70, s[26:27]
	v_cmp_ge_i32_e64 s[26:27], 10, v150
	v_cndmask_b32_e64 v71, v211, v71, s[28:29]
	v_cmp_ge_i32_e64 s[28:29], 11, v150
	v_cndmask_b32_e32 v72, v211, v72, vcc
	v_cmp_ge_i32_e32 vcc, 16, v150
	v_cndmask_b32_e64 v73, v211, v73, s[24:25]
	v_cmp_ge_i32_e64 s[24:25], 17, v150
	v_cndmask_b32_e64 v74, v211, v74, s[26:27]
	v_cmp_ge_i32_e64 s[26:27], 18, v150
	v_cndmask_b32_e64 v75, v211, v75, s[28:29]
	v_cmp_ge_i32_e64 s[28:29], 19, v150
	v_cndmask_b32_e32 v76, v211, v76, vcc
	v_cmp_ge_i32_e32 vcc, 24, v150
	v_cndmask_b32_e64 v77, v211, v77, s[24:25]
	v_cmp_ge_i32_e64 s[24:25], 25, v150
	v_cndmask_b32_e64 v78, v211, v78, s[26:27]
	v_cmp_ge_i32_e64 s[26:27], 26, v150
	v_cndmask_b32_e64 v79, v211, v79, s[28:29]
	v_cmp_ge_i32_e64 s[28:29], 27, v150
	v_cndmask_b32_e32 v80, v211, v80, vcc
	v_cndmask_b32_e64 v81, v211, v81, s[24:25]
	v_cndmask_b32_e64 v82, v211, v82, s[26:27]
	v_cndmask_b32_e64 v83, v211, v83, s[28:29]
	s_nop 0
	s_nop 1

; __device__ __forceinline__ void att_block(const bf16x8 (&kf)[4], const bf16x8 (&qf)[4], const bf16x8 (&va)[4], f32x16& o0, f32x16& o1, float& mrun, float& lrun, bool domask, int lo_, int hi_) {
;     f32x16 st;
; #pragma unroll
;     for (int i = 0; i < 16; ++i) st[i] = 0.f;
; #pragma unroll
;     for (int kk = 0; kk < 4; ++kk) st = __builtin_amdgcn_mfma_f32_32x32x16_bf16(kf[kk], qf[kk], st, 0, 0, 0);
;     if (domask) {
;         asm volatile("" : "+v"(lo_), "+v"(hi_));
; #pragma unroll
;         for (int i = 0; i < 16; ++i) { const int ci = (i & 3) + 8 * (i >> 2); st[i] = ((ci - lo_) | (hi_ - ci)) < 0 ? -INFINITY : st[i]; }
;     }
;     float bmax = -INFINITY;
; #pragma unroll
;     for (int i = 0; i < 16; ++i) bmax = fmaxf(bmax, st[i]);
;     bmax = fmaxf(bmax, __shfl_xor(bmax, 32));
;     const float mnew = fmaxf(mrun, bmax);
;     float lsum = 0.f;
; #pragma unroll
;     for (int i = 0; i < 16; ++i) { st[i] = __builtin_amdgcn_exp2f(st[i] - mnew); lsum += st[i]; }
;     lsum += __shfl_xor(lsum, 32);
;     const float alpha = __builtin_amdgcn_exp2f(mrun - mnew);
;     lrun = lrun * alpha + lsum; mrun = mnew;
; #pragma unroll
;     for (int i = 0; i < 16; ++i) { o0[i] *= alpha; o1[i] *= alpha; }
; #pragma unroll
;     for (int s = 0; s < 2; ++s) { v4u w; w.x = pk2(st[8 * s], st[8 * s + 1]); w.y = pk2(st[8 * s + 2], st[8 * s + 3]); w.z = pk2(st[8 * s + 4], st[8 * s + 5]); w.w = pk2(st[8 * s + 6], st[8 * s + 7]);
;         const bf16x8 pb = __builtin_bit_cast(bf16x8, w);
;         o0 = __builtin_amdgcn_mfma_f32_32x32x16_bf16(va[2 * s], pb, o0, 0, 0, 0);
;         o1 = __builtin_amdgcn_mfma_f32_32x32x16_bf16(va[2 * s + 1], pb, o1, 0, 0, 0); }
; __device__ __forceinline__ void att_phase(unsigned char* ws, LAS unsigned char* lds, int lane, int wave, int G) {
;     ...
;             asm volatile("s_waitcnt vmcnt(0)" ::: "memory");
;             if (kb < 5) ATT_DMA_KV(P, kb + 1, sb ^ 1);
;             else if (hn) ATT_DMA_KV(N, 0, sb ^ 1);
;             bf16x8 kf[4], va[4];
; #pragma unroll
;             for (int kk = 0; kk < 4; ++kk) kf[kk] = *(LAS const bf16x8*)(kfb + sb * 4096 + (((2 * kk + h) ^ (qc & 7)) << 4));
;             LAS const unsigned char* trs = trb + 8192 + sb * 4096;
; #pragma unroll
;             for (int s = 0; s < 2; ++s) {
;                 const s16x4 lo0 = vtr(trs + (16 * s) * VP), hi0 = vtr(trs + (16 * s + 8) * VP);
.LBB0_90:
	v_mul_lo_u32 v84, s52, v189
	s_mov_b32 s58, 0xff800000
	v_add_u32_e32 v198, s53, v84
	s_nop 7
	v_max3_f32 v84, v68, s58, v69
	v_max3_f32 v84, v84, v70, v71
	v_max3_f32 v84, v84, v72, v73
	v_max3_f32 v84, v84, v74, v75
	v_max3_f32 v84, v84, v76, v77
	v_max3_f32 v84, v84, v78, v79
	v_max3_f32 v84, v84, v80, v81
	v_max3_f32 v84, v84, v82, v83
	ds_bpermute_b32 v85, v201, v84
	s_waitcnt lgkmcnt(0)
	s_waitcnt lgkmcnt(0)
	v_max3_f32 v245, v148, v84, v85
	v_sub_f32_e32 v68, v68, v245
	v_exp_f32_e32 v149, v68
	v_sub_f32_e32 v69, v69, v245
	v_exp_f32_e32 v150, v69
	v_sub_f32_e32 v69, v70, v245
	v_exp_f32_e32 v151, v69
	v_sub_f32_e32 v69, v71, v245
	v_exp_f32_e32 v152, v69
	v_sub_f32_e32 v69, v72, v245
	v_add_f32_e32 v68, 0, v149
	v_exp_f32_e32 v153, v69
	v_sub_f32_e32 v69, v73, v245
	v_add_f32_e32 v68, v150, v68
	v_exp_f32_e32 v154, v69
	v_sub_f32_e32 v69, v74, v245
	v_add_f32_e32 v68, v151, v68
	v_exp_f32_e32 v155, v69
	v_sub_f32_e32 v69, v75, v245
	v_add_f32_e32 v68, v152, v68
	v_exp_f32_e32 v156, v69
	v_sub_f32_e32 v69, v76, v245
	v_add_f32_e32 v68, v153, v68
	v_exp_f32_e32 v157, v69
	v_sub_f32_e32 v69, v77, v245
	v_add_f32_e32 v68, v154, v68
	v_exp_f32_e32 v158, v69
	v_sub_f32_e32 v69, v78, v245
	v_add_f32_e32 v68, v155, v68
	v_exp_f32_e32 v159, v69
	v_sub_f32_e32 v69, v79, v245
	v_add_f32_e32 v68, v156, v68
	v_exp_f32_e32 v160, v69
	v_sub_f32_e32 v69, v80, v245
	v_add_f32_e32 v68, v157, v68
	v_exp_f32_e32 v161, v69
	v_sub_f32_e32 v69, v81, v245
	v_add_f32_e32 v68, v158, v68
	v_exp_f32_e32 v162, v69
	v_sub_f32_e32 v69, v82, v245
	v_add_f32_e32 v68, v159, v68
	v_exp_f32_e32 v163, v69
	v_sub_f32_e32 v69, v83, v245
	v_add_f32_e32 v68, v160, v68
	v_exp_f32_e32 v164, v69
	v_add_f32_e32 v68, v161, v68
	v_add_f32_e32 v68, v162, v68
	v_add_f32_e32 v68, v163, v68
	v_add_f32_e32 v241, v164, v68
	v_sub_f32_e32 v68, v148, v245
	v_exp_f32_e32 v194, v68
	ds_bpermute_b32 v242, v201, v241
	v_pk_mul_f32 v[82:83], v[50:51], v[194:195] op_sel_hi:[1,0]
	v_pk_mul_f32 v[80:81], v[48:49], v[194:195] op_sel_hi:[1,0]
	v_pk_mul_f32 v[78:79], v[46:47], v[194:195] op_sel_hi:[1,0]
	v_pk_mul_f32 v[76:77], v[44:45], v[194:195] op_sel_hi:[1,0]
	v_pk_mul_f32 v[74:75], v[42:43], v[194:195] op_sel_hi:[1,0]
	v_pk_mul_f32 v[72:73], v[40:41], v[194:195] op_sel_hi:[1,0]
	v_pk_mul_f32 v[70:71], v[38:39], v[194:195] op_sel_hi:[1,0]
	v_pk_mul_f32 v[68:69], v[36:37], v[194:195] op_sel_hi:[1,0]
	v_pk_mul_f32 v[98:99], v[66:67], v[194:195] op_sel_hi:[1,0]
	v_pk_mul_f32 v[96:97], v[64:65], v[194:195] op_sel_hi:[1,0]
	v_pk_mul_f32 v[94:95], v[62:63], v[194:195] op_sel_hi:[1,0]
	v_pk_mul_f32 v[92:93], v[60:61], v[194:195] op_sel_hi:[1,0]
	v_pk_mul_f32 v[90:91], v[58:59], v[194:195] op_sel_hi:[1,0]
	v_pk_mul_f32 v[88:89], v[56:57], v[194:195] op_sel_hi:[1,0]
	v_pk_mul_f32 v[86:87], v[54:55], v[194:195] op_sel_hi:[1,0]
	v_pk_mul_f32 v[84:85], v[52:53], v[194:195] op_sel_hi:[1,0]
	v_cvt_pk_bf16_f32 v36, v149, v150
	v_cvt_pk_bf16_f32 v37, v151, v152
	v_cvt_pk_bf16_f32 v38, v153, v154
	v_cvt_pk_bf16_f32 v39, v155, v156
	s_nop 1
	v_mfma_f32_32x32x16_bf16 v[68:83], v[144:147], v[36:39], v[68:83]
	v_mfma_f32_32x32x16_bf16 v[84:99], v[140:143], v[36:39], v[84:99]
	v_cvt_pk_bf16_f32 v36, v157, v158
	v_cvt_pk_bf16_f32 v37, v159, v160
	v_cvt_pk_bf16_f32 v38, v161, v162
	v_cvt_pk_bf16_f32 v39, v163, v164
	s_nop 1
	v_mfma_f32_32x32x16_bf16 v[68:83], v[136:139], v[36:39], v[68:83]
	v_mfma_f32_32x32x16_bf16 v[84:99], v[132:135], v[36:39], v[84:99]
	v_mul_lo_u32 v36, s56, v222
	v_add_u32_e32 v40, s11, v36
	v_max_i32_e32 v164, 0, v40
	s_waitcnt vmcnt(0)
	v_lshl_add_u32 v38, v164, 7, v180
	s_mov_b32 m0, s57
	v_add_u32_e32 v40, s6, v40
	global_load_lds_dwordx4 v38, s[98:99]
	v_lshl_add_u32 v36, v164, 7, v182
	s_mov_b32 m0, s7
	v_max_i32_e32 v164, 0, v40
	global_load_lds_dwordx4 v36, s[100:101]
	v_readlane_b32 s7, v254, 28
	v_lshl_add_u32 v38, v164, 7, v180
	s_mov_b32 m0, s7
	v_readlane_b32 s7, v254, 29
	v_add_u32_e32 v40, s6, v40
	global_load_lds_dwordx4 v38, s[98:99]
	v_lshl_add_u32 v36, v164, 7, v182
	s_mov_b32 m0, s7
	v_max_i32_e32 v164, 0, v40
	global_load_lds_dwordx4 v36, s[100:101]
	v_lshl_add_u32 v38, v164, 7, v180
	s_mov_b32 m0, s15
	v_lshl_add_u32 v36, v164, 7, v182
	global_load_lds_dwordx4 v38, s[98:99]
	s_mov_b32 m0, s17
	v_sub_u32_e32 v52, v199, v223
	global_load_lds_dwordx4 v36, s[100:101]
	v_add_u32_e32 v36, s6, v40
	v_max_i32_e32 v164, 0, v36
	v_lshl_add_u32 v38, v164, 7, v180
	s_mov_b32 m0, s21
	v_readlane_b32 s6, v254, 30
	global_load_lds_dwordx4 v38, s[98:99]
	v_lshl_add_u32 v36, v164, 7, v182
	s_mov_b32 m0, s6
	v_mov_b32_e32 v53, v224
	global_load_lds_dwordx4 v36, s[100:101]
	ds_read_b128 v[160:163], v225
	ds_read_b128 v[156:159], v226
	ds_read_b128 v[152:155], v227
	ds_read_b128 v[148:151], v228
	ds_read_b64_tr_b16 v[144:145], v229 offset:8192
	ds_read_b64_tr_b16 v[146:147], v229 offset:9216
	ds_read_b64_tr_b16 v[140:141], v229 offset:8256
	ds_read_b64_tr_b16 v[142:143], v229 offset:9280
	ds_read_b64_tr_b16 v[136:137], v229 offset:10240
	ds_read_b64_tr_b16 v[138:139], v229 offset:11264
	ds_read_b64_tr_b16 v[132:133], v229 offset:10304
	ds_read_b64_tr_b16 v[134:135], v229 offset:11328
	s_waitcnt lgkmcnt(0)
; __device__ __forceinline__ unsigned pk2(float lo, float hi) { return pg8::cvt_pk_bf16(lo, hi); }
; #define ATT_LOAD_Q(dst, J, set) do { const int qp_ = (J).pos0 + (32 * (set) + qc) * (J).d; _Pragma("unroll") for (int kk_ = 0; kk_ < 4; ++kk_) dst[kk_] = gld<bf16x8>(Qa + ((J).hb + (size_t)qp_) * 64 + 8 * h + 16 * kk_); } while (0)
; __device__ __forceinline__ void att_block(const bf16x8 (&kf)[4], const bf16x8 (&qf)[4], const bf16x8 (&va)[4], f32x16& o0, f32x16& o1, float& mrun, float& lrun, bool domask, int lo_, int hi_) {
;     f32x16 st;
; #pragma unroll
;     for (int i = 0; i < 16; ++i) st[i] = 0.f;
; #pragma unroll
;     for (int kk = 0; kk < 4; ++kk) st = __builtin_amdgcn_mfma_f32_32x32x16_bf16(kf[kk], qf[kk], st, 0, 0, 0);
;     if (domask) {
;         asm volatile("" : "+v"(lo_), "+v"(hi_));
; #pragma unroll
;         for (int i = 0; i < 16; ++i) { const int ci = (i & 3) + 8 * (i >> 2); st[i] = ((ci - lo_) | (hi_ - ci)) < 0 ? -INFINITY : st[i]; }
;     }
;     float bmax = -INFINITY;
; #pragma unroll
;     for (int i = 0; i < 16; ++i) bmax = fmaxf(bmax, st[i]);
;     bmax = fmaxf(bmax, __shfl_xor(bmax, 32));
;     const float mnew = fmaxf(mrun, bmax);
;     float lsum = 0.f;
; #pragma unroll
;     for (int i = 0; i < 16; ++i) { st[i] = __builtin_amdgcn_exp2f(st[i] - mnew); lsum += st[i]; }
;     lsum += __shfl_xor(lsum, 32);
;     const float alpha = __builtin_amdgcn_exp2f(mrun - mnew);
;     lrun = lrun * alpha + lsum; mrun = mnew;
; #pragma unroll
;     for (int i = 0; i < 16; ++i) { o0[i] *= alpha; o1[i] *= alpha; }
; #pragma unroll
;     for (int s = 0; s < 2; ++s) { v4u w; w.x = pk2(st[8 * s], st[8 * s + 1]); w.y = pk2(st[8 * s + 2], st[8 * s + 3]); w.z = pk2(st[8 * s + 4], st[8 * s + 5]); w.w = pk2(st[8 * s + 6], st[8 * s + 7]);
;         const bf16x8 pb = __builtin_bit_cast(bf16x8, w);
;         o0 = __builtin_amdgcn_mfma_f32_32x32x16_bf16(va[2 * s], pb, o0, 0, 0, 0);
;         o1 = __builtin_amdgcn_mfma_f32_32x32x16_bf16(va[2 * s + 1], pb, o1, 0, 0, 0); }
; __device__ __forceinline__ void att_phase(unsigned char* ws, LAS unsigned char* lds, int lane, int wave, int G) {
;     ...
;             if (kb <= 4) {
;                 att_block(kf, qfA, va, oA0, oA1, mA, lA, kb == 0 || kb == 4 || kminA > 32 * kb, mloA - 4 * h - 32 * kb, qc + 128 - 4 * h - 32 * kb);
;                 if (kb == 4 && hn) ATT_LOAD_Q(qfA, N, 0);
	v_mfma_f32_32x32x16_bf16 v[36:51], v[160:163], v[128:131], 0
	s_nop 0
	v_mfma_f32_32x32x16_bf16 v[36:51], v[156:159], v[124:127], v[36:51]
	v_mfma_f32_32x32x16_bf16 v[36:51], v[152:155], v[120:123], v[36:51]
	v_mfma_f32_32x32x16_bf16 v[36:51], v[148:151], v[116:119], v[36:51]
	s_nop 11
	v_cmp_le_i32_e32 vcc, 0, v53
	v_cmp_le_i32_e64 s[24:25], 1, v53
	v_cmp_le_i32_e64 s[26:27], 2, v53
	v_cmp_le_i32_e64 s[28:29], 3, v53
	v_cndmask_b32_e32 v36, v211, v36, vcc
	v_cmp_le_i32_e32 vcc, 8, v53
	v_cndmask_b32_e64 v37, v211, v37, s[24:25]
	v_cmp_le_i32_e64 s[24:25], 9, v53
	v_cndmask_b32_e64 v38, v211, v38, s[26:27]
	v_cmp_le_i32_e64 s[26:27], 10, v53
	v_cndmask_b32_e64 v39, v211, v39, s[28:29]
	v_cmp_le_i32_e64 s[28:29], 11, v53
	v_cndmask_b32_e32 v40, v211, v40, vcc
	v_cmp_le_i32_e32 vcc, 16, v53
	v_cndmask_b32_e64 v41, v211, v41, s[24:25]
	v_cmp_le_i32_e64 s[24:25], 17, v53
	v_cndmask_b32_e64 v42, v211, v42, s[26:27]
	v_cmp_le_i32_e64 s[26:27], 18, v53
	v_cndmask_b32_e64 v43, v211, v43, s[28:29]
	v_cmp_le_i32_e64 s[28:29], 19, v53
	v_cndmask_b32_e32 v44, v211, v44, vcc
	v_cmp_le_i32_e32 vcc, 24, v53
	v_cndmask_b32_e64 v45, v211, v45, s[24:25]
	v_cmp_le_i32_e64 s[24:25], 25, v53
	v_cndmask_b32_e64 v46, v211, v46, s[26:27]
	v_cmp_le_i32_e64 s[26:27], 26, v53
	v_cndmask_b32_e64 v47, v211, v47, s[28:29]
	v_cmp_le_i32_e64 s[28:29], 27, v53
	v_cndmask_b32_e32 v48, v211, v48, vcc
	v_cndmask_b32_e64 v49, v211, v49, s[24:25]
	v_cndmask_b32_e64 v50, v211, v50, s[26:27]
	v_cndmask_b32_e64 v51, v211, v51, s[28:29]
	s_nop 0
	v_max3_f32 v52, v36, s58, v37
	v_max3_f32 v52, v52, v38, v39
	v_max3_f32 v52, v52, v40, v41
	v_max3_f32 v52, v52, v42, v43
	v_max3_f32 v52, v52, v44, v45
	v_max3_f32 v52, v52, v46, v47
	v_max3_f32 v52, v52, v48, v49
	v_max3_f32 v52, v52, v50, v51
	ds_bpermute_b32 v53, v201, v52
	s_andn2_b64 vcc, exec, s[2:3]
	s_waitcnt lgkmcnt(0)
	v_max3_f32 v200, v202, v52, v53
	v_sub_f32_e32 v36, v36, v200
	v_exp_f32_e32 v164, v36
	v_sub_f32_e32 v37, v37, v200
	v_exp_f32_e32 v166, v37
	v_sub_f32_e32 v37, v38, v200
	v_exp_f32_e32 v167, v37
	v_sub_f32_e32 v37, v39, v200
	v_exp_f32_e32 v199, v37
	v_sub_f32_e32 v37, v40, v200
	v_add_f32_e32 v36, 0, v164
	v_exp_f32_e32 v248, v37
	v_sub_f32_e32 v37, v41, v200
	v_add_f32_e32 v36, v166, v36
	v_exp_f32_e32 v249, v37
	v_sub_f32_e32 v37, v42, v200
	v_add_f32_e32 v36, v167, v36
	v_exp_f32_e32 v250, v37
	v_sub_f32_e32 v37, v43, v200
	v_add_f32_e32 v36, v199, v36
	v_exp_f32_e32 v251, v37
	v_sub_f32_e32 v37, v44, v200
	v_add_f32_e32 v36, v248, v36
	v_exp_f32_e32 v252, v37
	v_sub_f32_e32 v37, v45, v200
	v_add_f32_e32 v36, v249, v36
	v_exp_f32_e32 v203, v37
	v_sub_f32_e32 v37, v46, v200
	v_add_f32_e32 v36, v250, v36
	v_exp_f32_e32 v168, v37
	v_sub_f32_e32 v37, v47, v200
	v_add_f32_e32 v36, v251, v36
	v_exp_f32_e32 v169, v37
	v_sub_f32_e32 v37, v48, v200
	v_add_f32_e32 v36, v252, v36
	v_exp_f32_e32 v212, v37
	v_sub_f32_e32 v37, v49, v200
	v_add_f32_e32 v36, v203, v36
	v_exp_f32_e32 v209, v37
	v_sub_f32_e32 v37, v50, v200
	v_add_f32_e32 v36, v168, v36
	v_exp_f32_e32 v197, v37
	v_sub_f32_e32 v37, v51, v200
	v_add_f32_e32 v36, v169, v36
	v_exp_f32_e32 v195, v37
	v_add_f32_e32 v36, v212, v36
	v_add_f32_e32 v36, v209, v36
	v_add_f32_e32 v36, v197, v36
	v_add_f32_e32 v246, v195, v36
	v_sub_f32_e32 v36, v202, v200
	v_exp_f32_e32 v202, v36
	ds_bpermute_b32 v247, v201, v246
	v_pk_mul_f32 v[66:67], v[18:19], v[202:203] op_sel_hi:[1,0]
	v_pk_mul_f32 v[64:65], v[16:17], v[202:203] op_sel_hi:[1,0]
	v_pk_mul_f32 v[62:63], v[14:15], v[202:203] op_sel_hi:[1,0]
	v_pk_mul_f32 v[60:61], v[12:13], v[202:203] op_sel_hi:[1,0]
	v_pk_mul_f32 v[58:59], v[10:11], v[202:203] op_sel_hi:[1,0]
	v_pk_mul_f32 v[56:57], v[8:9], v[202:203] op_sel_hi:[1,0]
	v_pk_mul_f32 v[54:55], v[6:7], v[202:203] op_sel_hi:[1,0]
	v_pk_mul_f32 v[52:53], v[4:5], v[202:203] op_sel_hi:[1,0]
	v_pk_mul_f32 v[50:51], v[34:35], v[202:203] op_sel_hi:[1,0]
	v_pk_mul_f32 v[48:49], v[32:33], v[202:203] op_sel_hi:[1,0]
	v_pk_mul_f32 v[46:47], v[30:31], v[202:203] op_sel_hi:[1,0]
	v_pk_mul_f32 v[44:45], v[28:29], v[202:203] op_sel_hi:[1,0]
	v_pk_mul_f32 v[42:43], v[26:27], v[202:203] op_sel_hi:[1,0]
	v_pk_mul_f32 v[40:41], v[24:25], v[202:203] op_sel_hi:[1,0]
	v_pk_mul_f32 v[38:39], v[22:23], v[202:203] op_sel_hi:[1,0]
	v_pk_mul_f32 v[36:37], v[20:21], v[202:203] op_sel_hi:[1,0]
	v_cvt_pk_bf16_f32 v4, v164, v166
	v_cvt_pk_bf16_f32 v5, v167, v199
	v_cvt_pk_bf16_f32 v6, v248, v249
	v_cvt_pk_bf16_f32 v7, v250, v251
	s_nop 1
	v_mfma_f32_32x32x16_bf16 v[52:67], v[144:147], v[4:7], v[52:67]
	v_mfma_f32_32x32x16_bf16 v[36:51], v[140:143], v[4:7], v[36:51]
	v_cvt_pk_bf16_f32 v4, v252, v203
	v_cvt_pk_bf16_f32 v5, v168, v169
	v_cvt_pk_bf16_f32 v6, v212, v209
	v_cvt_pk_bf16_f32 v7, v197, v195
	s_nop 1
	v_mfma_f32_32x32x16_bf16 v[52:67], v[136:139], v[4:7], v[52:67]
	v_mfma_f32_32x32x16_bf16 v[36:51], v[132:135], v[4:7], v[36:51]
	v_cndmask_b32_e64 v4, 0, 1, s[2:3]
	v_cmp_ne_u32_e64 s[6:7], 1, v4
	s_cbranch_vccnz .LBB0_92
	v_ashrrev_i32_e32 v199, 31, v198
	v_lshl_add_u64 v[4:5], s[0:1], 0, v[198:199]
	v_lshlrev_b64 v[4:5], 7, v[4:5]
	v_lshl_add_u64 v[4:5], v[186:187], 0, v[4:5]
	global_load_dwordx4 v[128:131], v[4:5], off
	global_load_dwordx4 v[124:127], v[4:5], off offset:32
	global_load_dwordx4 v[120:123], v[4:5], off offset:64
	global_load_dwordx4 v[116:119], v[4:5], off offset:96

; __device__ __forceinline__ void att_block(const bf16x8 (&kf)[4], const bf16x8 (&qf)[4], const bf16x8 (&va)[4], f32x16& o0, f32x16& o1, float& mrun, float& lrun, bool domask, int lo_, int hi_) {
;     f32x16 st;
; #pragma unroll
;     for (int i = 0; i < 16; ++i) st[i] = 0.f;
; #pragma unroll
;     for (int kk = 0; kk < 4; ++kk) st = __builtin_amdgcn_mfma_f32_32x32x16_bf16(kf[kk], qf[kk], st, 0, 0, 0);
;     if (domask) {
;         asm volatile("" : "+v"(lo_), "+v"(hi_));
; #pragma unroll
;         for (int i = 0; i < 16; ++i) { const int ci = (i & 3) + 8 * (i >> 2); st[i] = ((ci - lo_) | (hi_ - ci)) < 0 ? -INFINITY : st[i]; }
;     }
;     float bmax = -INFINITY;
; #pragma unroll
;     for (int i = 0; i < 16; ++i) bmax = fmaxf(bmax, st[i]);
;     bmax = fmaxf(bmax, __shfl_xor(bmax, 32));
;     const float mnew = fmaxf(mrun, bmax);
;     float lsum = 0.f;
; #pragma unroll
;     for (int i = 0; i < 16; ++i) { st[i] = __builtin_amdgcn_exp2f(st[i] - mnew); lsum += st[i]; }
;     lsum += __shfl_xor(lsum, 32);
; __device__ __forceinline__ void att_phase(unsigned char* ws, LAS unsigned char* lds, int lane, int wave, int G) {
;     ...
;             bf16x8 kf[4], va[4];
; #pragma unroll
;             for (int kk = 0; kk < 4; ++kk) kf[kk] = *(LAS const bf16x8*)(kfb + sb * 4096 + (((2 * kk + h) ^ (qc & 7)) << 4));
;             LAS const unsigned char* trs = trb + 8192 + sb * 4096;
; #pragma unroll
;             for (int s = 0; s < 2; ++s) {
;                 const s16x4 lo0 = vtr(trs + (16 * s) * VP), hi0 = vtr(trs + (16 * s + 8) * VP);
;                 const s16x4 lo1 = vtr(trs + (16 * s) * VP + 64), hi1 = vtr(trs + (16 * s + 8) * VP + 64);
;                 va[2 * s] = (bf16x8){lo0[0], lo0[1], lo0[2], lo0[3], hi0[0], hi0[1], hi0[2], hi0[3]};
;                 va[2 * s + 1] = (bf16x8){lo1[0], lo1[1], lo1[2], lo1[3], hi1[0], hi1[1], hi1[2], hi1[3]};
;             }
;             if (kb <= 4) {
;                 att_block(kf, qfA, va, oA0, oA1, mA, lA, kb == 0 || kb == 4 || kminA > 32 * kb, mloA - 4 * h - 32 * kb, qc + 128 - 4 * h - 32 * kb);
;                 if (kb == 4 && hn) ATT_LOAD_Q(qfA, N, 0);
;             }
;             if (kb >= 1) {
;                 att_block(kf, qfB, va, oB0, oB1, mB, lB, kb == 1 || kb == 5 || kminB > 32 * (kb - 1), mloB - 4 * h - 32 * (kb - 1), qc + 128 - 4 * h - 32 * (kb - 1));
;                 if (kb == 5 && hn) ATT_LOAD_Q(qfB, N, 1);
.LBB0_96:
	ds_read_b128 v[68:71], v225 offset:4096
	ds_read_b128 v[132:135], v226 offset:4096
	ds_read_b128 v[136:139], v227 offset:4096
	ds_read_b128 v[140:143], v228 offset:4096
	ds_read_b64_tr_b16 v[92:93], v229 offset:12288
	ds_read_b64_tr_b16 v[94:95], v229 offset:13312
	ds_read_b64_tr_b16 v[86:87], v229 offset:13376
	ds_read_b64_tr_b16 v[84:85], v229 offset:12352
	s_waitcnt lgkmcnt(0)
	v_mfma_f32_32x32x16_bf16 v[68:83], v[68:71], v[112:115], 0
	v_sub_u32_e32 v144, v237, v223
	v_mov_b32_e32 v145, v224
	ds_read_b64_tr_b16 v[96:97], v229 offset:14336
	ds_read_b64_tr_b16 v[98:99], v229 offset:15360
	ds_read_b64_tr_b16 v[90:91], v229 offset:15424
	ds_read_b64_tr_b16 v[88:89], v229 offset:14400
	s_mov_b32 s14, 0xff800000
	v_mfma_f32_32x32x16_bf16 v[68:83], v[132:135], v[108:111], v[68:83]
	v_mfma_f32_32x32x16_bf16 v[68:83], v[136:139], v[104:107], v[68:83]
	v_mfma_f32_32x32x16_bf16 v[68:83], v[140:143], v[100:103], v[68:83]
	s_nop 11
	v_cmp_le_i32_e32 vcc, 0, v145
	v_cmp_le_i32_e64 s[24:25], 1, v145
	v_cmp_le_i32_e64 s[26:27], 2, v145
	v_cmp_le_i32_e64 s[28:29], 3, v145
	v_cndmask_b32_e32 v68, v211, v68, vcc
	v_cmp_le_i32_e32 vcc, 8, v145
	v_cndmask_b32_e64 v69, v211, v69, s[24:25]
	v_cmp_le_i32_e64 s[24:25], 9, v145
	v_cndmask_b32_e64 v70, v211, v70, s[26:27]
	v_cmp_le_i32_e64 s[26:27], 10, v145
	v_cndmask_b32_e64 v71, v211, v71, s[28:29]
	v_cmp_le_i32_e64 s[28:29], 11, v145
	v_cndmask_b32_e32 v72, v211, v72, vcc
	v_cmp_le_i32_e32 vcc, 16, v145
	v_cndmask_b32_e64 v73, v211, v73, s[24:25]
	v_cmp_le_i32_e64 s[24:25], 17, v145
	v_cndmask_b32_e64 v74, v211, v74, s[26:27]
	v_cmp_le_i32_e64 s[26:27], 18, v145
	v_cndmask_b32_e64 v75, v211, v75, s[28:29]
	v_cmp_le_i32_e64 s[28:29], 19, v145
	v_cndmask_b32_e32 v132, v211, v76, vcc
	v_cmp_le_i32_e32 vcc, 24, v145
	v_cndmask_b32_e64 v77, v211, v77, s[24:25]
	v_cmp_le_i32_e64 s[24:25], 25, v145
	v_cndmask_b32_e64 v78, v211, v78, s[26:27]
	v_cmp_le_i32_e64 s[26:27], 26, v145
	v_cndmask_b32_e64 v79, v211, v79, s[28:29]
	v_cmp_le_i32_e64 s[28:29], 27, v145
	v_cndmask_b32_e32 v80, v211, v80, vcc
	v_cndmask_b32_e64 v81, v211, v81, s[24:25]
	v_cndmask_b32_e64 v82, v211, v82, s[26:27]
	v_cndmask_b32_e64 v83, v211, v83, s[28:29]
	s_nop 0
	s_nop 1
	s_nop 1
	s_nop 0
	v_max3_f32 v76, v68, s14, v69
	v_max3_f32 v76, v76, v70, v71
	v_max3_f32 v76, v76, v72, v73
	v_max3_f32 v76, v76, v74, v75
	v_max3_f32 v76, v76, v132, v77
	v_max3_f32 v76, v76, v78, v79
	v_max3_f32 v76, v76, v80, v81
	v_max3_f32 v76, v76, v82, v83
	ds_bpermute_b32 v133, v201, v76
	s_and_b64 vcc, exec, s[6:7]
	s_waitcnt lgkmcnt(0)
	v_max3_f32 v76, v151, v76, v133
	v_sub_f32_e32 v68, v68, v76
	v_exp_f32_e32 v68, v68
	v_sub_f32_e32 v69, v69, v76
	v_exp_f32_e32 v69, v69
	v_sub_f32_e32 v70, v70, v76
	v_exp_f32_e32 v70, v70
	v_sub_f32_e32 v71, v71, v76
	v_exp_f32_e32 v71, v71
	v_sub_f32_e32 v72, v72, v76
	v_add_f32_e32 v133, 0, v68
	v_exp_f32_e32 v72, v72
	v_sub_f32_e32 v73, v73, v76
	v_add_f32_e32 v133, v69, v133
	v_exp_f32_e32 v73, v73
	v_sub_f32_e32 v74, v74, v76
	v_add_f32_e32 v133, v70, v133
	v_exp_f32_e32 v74, v74
	v_sub_f32_e32 v75, v75, v76
	v_add_f32_e32 v133, v71, v133
	v_exp_f32_e32 v75, v75
	v_sub_f32_e32 v132, v132, v76
	v_add_f32_e32 v133, v72, v133
	v_exp_f32_e32 v132, v132
	v_sub_f32_e32 v77, v77, v76
	v_add_f32_e32 v133, v73, v133
	v_exp_f32_e32 v77, v77
	v_sub_f32_e32 v78, v78, v76
	v_add_f32_e32 v133, v74, v133
	v_exp_f32_e32 v134, v78
	v_add_f32_e32 v78, v75, v133
	v_add_f32_e32 v78, v132, v78
	v_add_f32_e32 v78, v77, v78
	v_add_f32_e32 v133, v134, v78
	v_sub_f32_e32 v78, v79, v76
	v_exp_f32_e32 v79, v78
	v_sub_f32_e32 v78, v80, v76
	v_exp_f32_e32 v80, v78
	v_sub_f32_e32 v78, v151, v76
	v_exp_f32_e32 v78, v78
	v_cvt_pk_bf16_f32 v68, v68, v69
	v_cvt_pk_bf16_f32 v69, v70, v71
	v_cvt_pk_bf16_f32 v70, v72, v73
	v_pk_mul_f32 v[34:35], v[34:35], v[78:79] op_sel_hi:[1,0]
	v_pk_mul_f32 v[32:33], v[32:33], v[78:79] op_sel_hi:[1,0]
	v_pk_mul_f32 v[30:31], v[30:31], v[78:79] op_sel_hi:[1,0]
	v_pk_mul_f32 v[28:29], v[28:29], v[78:79] op_sel_hi:[1,0]
	v_pk_mul_f32 v[26:27], v[26:27], v[78:79] op_sel_hi:[1,0]
	v_pk_mul_f32 v[24:25], v[24:25], v[78:79] op_sel_hi:[1,0]
	v_pk_mul_f32 v[22:23], v[22:23], v[78:79] op_sel_hi:[1,0]
	v_pk_mul_f32 v[20:21], v[20:21], v[78:79] op_sel_hi:[1,0]
	v_pk_mul_f32 v[18:19], v[18:19], v[78:79] op_sel_hi:[1,0]
	v_cvt_pk_bf16_f32 v71, v74, v75
	v_pk_mul_f32 v[16:17], v[16:17], v[78:79] op_sel_hi:[1,0]
	v_pk_mul_f32 v[14:15], v[14:15], v[78:79] op_sel_hi:[1,0]
	v_pk_mul_f32 v[12:13], v[12:13], v[78:79] op_sel_hi:[1,0]
	v_pk_mul_f32 v[10:11], v[10:11], v[78:79] op_sel_hi:[1,0]
	v_pk_mul_f32 v[8:9], v[8:9], v[78:79] op_sel_hi:[1,0]
	v_pk_mul_f32 v[6:7], v[6:7], v[78:79] op_sel_hi:[1,0]
	v_pk_mul_f32 v[4:5], v[4:5], v[78:79] op_sel_hi:[1,0]
	v_mfma_f32_32x32x16_bf16 v[20:35], v[92:95], v[68:71], v[20:35]
	v_sub_f32_e32 v81, v81, v76
	v_sub_f32_e32 v82, v82, v76
	v_exp_f32_e32 v81, v81
	v_exp_f32_e32 v72, v82
	v_add_f32_e32 v74, v79, v133
	v_add_f32_e32 v74, v80, v74
	v_add_f32_e32 v74, v81, v74
	v_mfma_f32_32x32x16_bf16 v[4:19], v[84:87], v[68:71], v[4:19]
	v_sub_f32_e32 v68, v83, v76
	v_exp_f32_e32 v73, v68
	v_cvt_pk_bf16_f32 v68, v132, v77
	v_cvt_pk_bf16_f32 v69, v134, v79
	v_cvt_pk_bf16_f32 v70, v80, v81
	v_cvt_pk_bf16_f32 v71, v72, v73
	v_add_f32_e32 v72, v72, v74
	v_add_f32_e32 v77, v73, v72
	v_mfma_f32_32x32x16_bf16 v[20:35], v[96:99], v[68:71], v[20:35]
	ds_bpermute_b32 v79, v201, v77
	v_mfma_f32_32x32x16_bf16 v[4:19], v[88:91], v[68:71], v[4:19]
	s_cbranch_vccnz .LBB0_98
	v_lshl_add_u32 v68, s52, 5, v198
	v_ashrrev_i32_e32 v69, 31, v68
	v_lshl_add_u64 v[68:69], s[0:1], 0, v[68:69]
	v_lshlrev_b64 v[68:69], 7, v[68:69]
	v_lshl_add_u64 v[68:69], v[186:187], 0, v[68:69]
	global_load_dwordx4 v[112:115], v[68:69], off
	global_load_dwordx4 v[108:111], v[68:69], off offset:32
	global_load_dwordx4 v[104:107], v[68:69], off offset:64
	global_load_dwordx4 v[100:103], v[68:69], off offset:96
